# v114 + RESID epilogue first half: vmcnt(0) after the 8 residual loads replaced by graded counted waits before each load's first use
# speedup vs baseline: 1.0014x; 1.0014x over previous
.LBB0_649:
	s_add_i32 s42, s4, 2
	s_add_i32 s43, 0, 0x10000
	s_cmp_eq_u32 s35, s4
	v_lshl_add_u64 v[132:133], v[130:131], 0, s[84:85]
	s_cselect_b64 vcc, -1, 0
	v_add_u32_e32 v144, s43, v237
	v_cndmask_b32_e32 v157, v133, v177, vcc
	v_cndmask_b32_e32 v156, v132, v176, vcc
	ds_read_b128 v[132:135], v144
	ds_read_b128 v[136:139], v144 offset:1024
	ds_read_b128 v[140:143], v144 offset:2048
	ds_read_b128 v[144:147], v144 offset:3072
	s_cselect_b32 s4, s0, s6
	s_cselect_b32 s5, s1, s7
	v_lshl_add_u64 v[202:203], v[130:131], 0, v[172:173]
	s_add_i32 m0, s8, 0xc000
	ds_read_b128 v[148:151], v243
	ds_read_b128 v[152:155], v243 offset:1024
	ds_read_b128 v[178:181], v243 offset:2048
	ds_read_b128 v[182:185], v243 offset:3072
	ds_read_b128 v[186:189], v243 offset:4096
	ds_read_b128 v[190:193], v243 offset:5120
	ds_read_b128 v[194:197], v243 offset:6144
	ds_read_b128 v[198:201], v243 offset:7168
	global_load_lds_dwordx4 v[202:203], off
	v_lshl_add_u64 v[202:203], v[130:131], 0, v[174:175]
	s_add_i32 m0, s8, 0xe000
	s_nop 0
	global_load_lds_dwordx4 v[202:203], off
	s_waitcnt lgkmcnt(8)
	s_barrier
	s_waitcnt lgkmcnt(0)
	s_waitcnt lgkmcnt(0)
	v_mfma_f32_16x16x32_bf16 v[126:129], v[132:135], v[148:151], v[126:129]
	v_mfma_f32_16x16x32_bf16 v[122:125], v[140:143], v[148:151], v[122:125]
	v_mfma_f32_16x16x32_bf16 v[110:113], v[132:135], v[178:181], v[110:113]
	v_mfma_f32_16x16x32_bf16 v[106:109], v[140:143], v[178:181], v[106:109]
	v_mfma_f32_16x16x32_bf16 v[98:101], v[132:135], v[186:189], v[98:101]
	v_mfma_f32_16x16x32_bf16 v[90:93], v[140:143], v[186:189], v[90:93]
	v_mfma_f32_16x16x32_bf16 v[82:85], v[132:135], v[194:197], v[82:85]
	v_mfma_f32_16x16x32_bf16 v[74:77], v[140:143], v[194:197], v[74:77]
	v_mfma_f32_16x16x32_bf16 v[126:129], v[136:139], v[152:155], v[126:129]
	v_mfma_f32_16x16x32_bf16 v[122:125], v[144:147], v[152:155], v[122:125]
	v_mfma_f32_16x16x32_bf16 v[110:113], v[136:139], v[182:185], v[110:113]
	v_mfma_f32_16x16x32_bf16 v[106:109], v[144:147], v[182:185], v[106:109]
	v_mfma_f32_16x16x32_bf16 v[98:101], v[136:139], v[190:193], v[98:101]
	v_mfma_f32_16x16x32_bf16 v[90:93], v[144:147], v[190:193], v[90:93]
	v_mfma_f32_16x16x32_bf16 v[82:85], v[136:139], v[198:201], v[82:85]
	v_mfma_f32_16x16x32_bf16 v[74:77], v[144:147], v[198:201], v[74:77]
	s_barrier
	s_add_i32 s89, 0, 0x14000
	s_add_i32 s43, s43, s3
	v_add_u32_e32 v169, s89, v237
	v_lshl_add_u64 v[218:219], s[4:5], 0, v[162:163]
	s_mov_b32 m0, s43
	ds_read_b128 v[202:205], v169
	ds_read_b128 v[206:209], v169 offset:1024
	ds_read_b128 v[210:213], v169 offset:2048
	ds_read_b128 v[214:217], v169 offset:3072
	global_load_lds_dwordx4 v[218:219], off
	v_lshl_add_u64 v[224:225], s[4:5], 0, v[166:167]
	s_add_i32 m0, s43, 0x2000
	s_nop 0
	global_load_lds_dwordx4 v[224:225], off
	s_barrier
	s_waitcnt lgkmcnt(0)
	s_waitcnt lgkmcnt(0)
	v_mfma_f32_16x16x32_bf16 v[118:121], v[202:205], v[148:151], v[118:121]
	v_mfma_f32_16x16x32_bf16 v[114:117], v[210:213], v[148:151], v[114:117]
	v_mfma_f32_16x16x32_bf16 v[102:105], v[202:205], v[178:181], v[102:105]
	v_mfma_f32_16x16x32_bf16 v[94:97], v[210:213], v[178:181], v[94:97]
	v_mfma_f32_16x16x32_bf16 v[86:89], v[202:205], v[186:189], v[86:89]
	v_mfma_f32_16x16x32_bf16 v[78:81], v[210:213], v[186:189], v[78:81]
	v_mfma_f32_16x16x32_bf16 v[70:73], v[202:205], v[194:197], v[70:73]
	v_mfma_f32_16x16x32_bf16 v[66:69], v[210:213], v[194:197], v[66:69]
	v_mfma_f32_16x16x32_bf16 v[118:121], v[206:209], v[152:155], v[118:121]
	v_mfma_f32_16x16x32_bf16 v[114:117], v[214:217], v[152:155], v[114:117]
	v_mfma_f32_16x16x32_bf16 v[102:105], v[206:209], v[182:185], v[102:105]
	v_mfma_f32_16x16x32_bf16 v[94:97], v[214:217], v[182:185], v[94:97]
	v_mfma_f32_16x16x32_bf16 v[86:89], v[206:209], v[190:193], v[86:89]
	v_mfma_f32_16x16x32_bf16 v[78:81], v[214:217], v[190:193], v[78:81]
	v_mfma_f32_16x16x32_bf16 v[70:73], v[206:209], v[198:201], v[70:73]
	v_mfma_f32_16x16x32_bf16 v[66:69], v[214:217], v[198:201], v[66:69]
	s_mov_b32 m0, s8
	v_lshl_add_u64 v[230:231], v[156:157], 0, v[160:161]
	s_barrier
	ds_read_b128 v[148:151], v243 offset:16384
	ds_read_b128 v[152:155], v243 offset:17408
	ds_read_b128 v[178:181], v243 offset:18432
	ds_read_b128 v[182:185], v243 offset:19456
	ds_read_b128 v[186:189], v243 offset:20480
	ds_read_b128 v[190:193], v243 offset:21504
	ds_read_b128 v[194:197], v243 offset:22528
	ds_read_b128 v[198:201], v243 offset:23552
	global_load_lds_dwordx4 v[230:231], off
	v_lshl_add_u64 v[232:233], v[156:157], 0, v[164:165]
	s_mov_b32 m0, s9
	s_nop 0
	global_load_lds_dwordx4 v[232:233], off
	s_barrier
	s_waitcnt lgkmcnt(0)
	s_waitcnt lgkmcnt(0)
	v_mfma_f32_16x16x32_bf16 v[62:65], v[132:135], v[148:151], v[62:65]
	v_mfma_f32_16x16x32_bf16 v[58:61], v[140:143], v[148:151], v[58:61]
	v_mfma_f32_16x16x32_bf16 v[46:49], v[132:135], v[178:181], v[46:49]
	v_mfma_f32_16x16x32_bf16 v[42:45], v[140:143], v[178:181], v[42:45]
	v_mfma_f32_16x16x32_bf16 v[34:37], v[132:135], v[186:189], v[34:37]
	v_mfma_f32_16x16x32_bf16 v[26:29], v[140:143], v[186:189], v[26:29]
	v_mfma_f32_16x16x32_bf16 v[18:21], v[132:135], v[194:197], v[18:21]
	v_mfma_f32_16x16x32_bf16 v[10:13], v[140:143], v[194:197], v[10:13]
	v_mfma_f32_16x16x32_bf16 v[62:65], v[136:139], v[152:155], v[62:65]
	v_mfma_f32_16x16x32_bf16 v[58:61], v[144:147], v[152:155], v[58:61]
	v_mfma_f32_16x16x32_bf16 v[46:49], v[136:139], v[182:185], v[46:49]
	v_mfma_f32_16x16x32_bf16 v[42:45], v[144:147], v[182:185], v[42:45]
	v_mfma_f32_16x16x32_bf16 v[34:37], v[136:139], v[190:193], v[34:37]
	v_mfma_f32_16x16x32_bf16 v[26:29], v[144:147], v[190:193], v[26:29]
	v_mfma_f32_16x16x32_bf16 v[18:21], v[136:139], v[198:201], v[18:21]
	v_mfma_f32_16x16x32_bf16 v[10:13], v[144:147], v[198:201], v[10:13]
	s_barrier
	s_add_u32 s4, s4, s94
	s_addc_u32 s5, s5, 0
	s_add_i32 s43, s89, s3
	v_lshl_add_u64 v[244:245], s[4:5], 0, v[162:163]
	s_mov_b32 m0, s43
	v_lshl_add_u64 v[246:247], s[4:5], 0, v[166:167]
	global_load_lds_dwordx4 v[244:245], off
	s_add_i32 m0, s43, 0x2000
	s_nop 0
	global_load_lds_dwordx4 v[246:247], off
	s_waitcnt vmcnt(6)
	s_barrier
	v_mfma_f32_16x16x32_bf16 v[54:57], v[202:205], v[148:151], v[54:57]
	v_mfma_f32_16x16x32_bf16 v[50:53], v[210:213], v[148:151], v[50:53]
	v_mfma_f32_16x16x32_bf16 v[38:41], v[202:205], v[178:181], v[38:41]
	v_mfma_f32_16x16x32_bf16 v[30:33], v[210:213], v[178:181], v[30:33]
	v_mfma_f32_16x16x32_bf16 v[22:25], v[202:205], v[186:189], v[22:25]
	v_mfma_f32_16x16x32_bf16 v[14:17], v[210:213], v[186:189], v[14:17]
	v_mfma_f32_16x16x32_bf16 v[6:9], v[202:205], v[194:197], v[6:9]
	v_mfma_f32_16x16x32_bf16 v[2:5], v[210:213], v[194:197], v[2:5]
	v_mfma_f32_16x16x32_bf16 v[54:57], v[206:209], v[152:155], v[54:57]
	v_mfma_f32_16x16x32_bf16 v[50:53], v[214:217], v[152:155], v[50:53]
	v_mfma_f32_16x16x32_bf16 v[38:41], v[206:209], v[182:185], v[38:41]
	v_mfma_f32_16x16x32_bf16 v[30:33], v[214:217], v[182:185], v[30:33]
	v_mfma_f32_16x16x32_bf16 v[22:25], v[206:209], v[190:193], v[22:25]
	v_mfma_f32_16x16x32_bf16 v[14:17], v[214:217], v[190:193], v[14:17]
	v_mfma_f32_16x16x32_bf16 v[6:9], v[206:209], v[198:201], v[6:9]
	v_mfma_f32_16x16x32_bf16 v[2:5], v[214:217], v[198:201], v[2:5]
	s_add_i32 s4, 0, 0x18000
	v_add_u32_e32 v144, s4, v237
	s_barrier
	ds_read_b128 v[132:135], v144
	ds_read_b128 v[136:139], v144 offset:1024
	ds_read_b128 v[140:143], v144 offset:2048
	ds_read_b128 v[144:147], v144 offset:3072
	v_lshl_add_u64 v[156:157], v[156:157], 0, s[94:95]
	s_mov_b32 m0, s10
	v_lshl_add_u64 v[202:203], v[156:157], 0, v[160:161]
	ds_read_b128 v[148:151], v243 offset:32768
	ds_read_b128 v[152:155], v243 offset:33792
	ds_read_b128 v[178:181], v243 offset:34816
	ds_read_b128 v[182:185], v243 offset:35840
	ds_read_b128 v[186:189], v243 offset:36864
	ds_read_b128 v[190:193], v243 offset:37888
	ds_read_b128 v[194:197], v243 offset:38912
	ds_read_b128 v[198:201], v243 offset:39936
	global_load_lds_dwordx4 v[202:203], off
	v_lshl_add_u64 v[156:157], v[156:157], 0, v[164:165]
	s_mov_b32 m0, s11
	s_nop 0
	global_load_lds_dwordx4 v[156:157], off
	s_waitcnt lgkmcnt(8)
	s_barrier
	s_waitcnt lgkmcnt(0)
	s_waitcnt lgkmcnt(0)
	v_mfma_f32_16x16x32_bf16 v[126:129], v[132:135], v[148:151], v[126:129]
	v_mfma_f32_16x16x32_bf16 v[122:125], v[140:143], v[148:151], v[122:125]
	v_mfma_f32_16x16x32_bf16 v[110:113], v[132:135], v[178:181], v[110:113]
	v_mfma_f32_16x16x32_bf16 v[106:109], v[140:143], v[178:181], v[106:109]
	v_mfma_f32_16x16x32_bf16 v[98:101], v[132:135], v[186:189], v[98:101]
	v_mfma_f32_16x16x32_bf16 v[90:93], v[140:143], v[186:189], v[90:93]
	v_mfma_f32_16x16x32_bf16 v[82:85], v[132:135], v[194:197], v[82:85]
	v_mfma_f32_16x16x32_bf16 v[74:77], v[140:143], v[194:197], v[74:77]
	v_mfma_f32_16x16x32_bf16 v[126:129], v[136:139], v[152:155], v[126:129]
	v_mfma_f32_16x16x32_bf16 v[122:125], v[144:147], v[152:155], v[122:125]
	v_mfma_f32_16x16x32_bf16 v[110:113], v[136:139], v[182:185], v[110:113]
	v_mfma_f32_16x16x32_bf16 v[106:109], v[144:147], v[182:185], v[106:109]
	v_mfma_f32_16x16x32_bf16 v[98:101], v[136:139], v[190:193], v[98:101]
	v_mfma_f32_16x16x32_bf16 v[90:93], v[144:147], v[190:193], v[90:93]
	v_mfma_f32_16x16x32_bf16 v[82:85], v[136:139], v[198:201], v[82:85]
	v_mfma_f32_16x16x32_bf16 v[74:77], v[144:147], v[198:201], v[74:77]
	s_barrier
	s_add_i32 s5, 0, 0x1c000
	v_add_u32_e32 v156, s5, v237
	s_add_i32 s4, s4, s3
	ds_read_b128 v[202:205], v156
	ds_read_b128 v[206:209], v156 offset:1024
	ds_read_b128 v[210:213], v156 offset:2048
	ds_read_b128 v[214:217], v156 offset:3072
	s_add_i32 m0, s4, 0xffffff80
	s_nop 0
	global_load_lds_dwordx4 v[218:219], off offset:128
	s_add_i32 m0, s4, 0x1f80
	s_nop 0
	global_load_lds_dwordx4 v[224:225], off offset:128
	s_barrier
	s_waitcnt lgkmcnt(0)
	s_waitcnt lgkmcnt(0)
	v_mfma_f32_16x16x32_bf16 v[118:121], v[202:205], v[148:151], v[118:121]
	v_mfma_f32_16x16x32_bf16 v[114:117], v[210:213], v[148:151], v[114:117]
	v_mfma_f32_16x16x32_bf16 v[102:105], v[202:205], v[178:181], v[102:105]
	v_mfma_f32_16x16x32_bf16 v[94:97], v[210:213], v[178:181], v[94:97]
	v_mfma_f32_16x16x32_bf16 v[86:89], v[202:205], v[186:189], v[86:89]
	v_mfma_f32_16x16x32_bf16 v[78:81], v[210:213], v[186:189], v[78:81]
	v_mfma_f32_16x16x32_bf16 v[70:73], v[202:205], v[194:197], v[70:73]
	v_mfma_f32_16x16x32_bf16 v[66:69], v[210:213], v[194:197], v[66:69]
	v_mfma_f32_16x16x32_bf16 v[118:121], v[206:209], v[152:155], v[118:121]
	v_mfma_f32_16x16x32_bf16 v[114:117], v[214:217], v[152:155], v[114:117]
	v_mfma_f32_16x16x32_bf16 v[102:105], v[206:209], v[182:185], v[102:105]
	v_mfma_f32_16x16x32_bf16 v[94:97], v[214:217], v[182:185], v[94:97]
	v_mfma_f32_16x16x32_bf16 v[86:89], v[206:209], v[190:193], v[86:89]
	v_mfma_f32_16x16x32_bf16 v[78:81], v[214:217], v[190:193], v[78:81]
	v_mfma_f32_16x16x32_bf16 v[70:73], v[206:209], v[198:201], v[70:73]
	v_mfma_f32_16x16x32_bf16 v[66:69], v[214:217], v[198:201], v[66:69]
	s_add_i32 m0, s12, 0xffffff80
	s_barrier
	ds_read_b128 v[148:151], v243 offset:49152
	ds_read_b128 v[152:155], v243 offset:50176
	ds_read_b128 v[178:181], v243 offset:51200
	ds_read_b128 v[182:185], v243 offset:52224
	ds_read_b128 v[186:189], v243 offset:53248
	ds_read_b128 v[190:193], v243 offset:54272
	ds_read_b128 v[194:197], v243 offset:55296
	ds_read_b128 v[198:201], v243 offset:56320
	global_load_lds_dwordx4 v[230:231], off offset:128
	s_add_i32 m0, s28, 0xffffff80
	s_nop 0
	global_load_lds_dwordx4 v[232:233], off offset:128
	s_barrier
	s_waitcnt lgkmcnt(0)
	s_waitcnt lgkmcnt(0)
	v_mfma_f32_16x16x32_bf16 v[62:65], v[132:135], v[148:151], v[62:65]
	v_mfma_f32_16x16x32_bf16 v[58:61], v[140:143], v[148:151], v[58:61]
	v_mfma_f32_16x16x32_bf16 v[46:49], v[132:135], v[178:181], v[46:49]
	v_mfma_f32_16x16x32_bf16 v[42:45], v[140:143], v[178:181], v[42:45]
	v_mfma_f32_16x16x32_bf16 v[34:37], v[132:135], v[186:189], v[34:37]
	v_mfma_f32_16x16x32_bf16 v[26:29], v[140:143], v[186:189], v[26:29]
	v_mfma_f32_16x16x32_bf16 v[18:21], v[132:135], v[194:197], v[18:21]
	v_mfma_f32_16x16x32_bf16 v[10:13], v[140:143], v[194:197], v[10:13]
	v_mfma_f32_16x16x32_bf16 v[62:65], v[136:139], v[152:155], v[62:65]
	v_mfma_f32_16x16x32_bf16 v[58:61], v[144:147], v[152:155], v[58:61]
	v_mfma_f32_16x16x32_bf16 v[46:49], v[136:139], v[182:185], v[46:49]
	v_mfma_f32_16x16x32_bf16 v[42:45], v[144:147], v[182:185], v[42:45]
	v_mfma_f32_16x16x32_bf16 v[34:37], v[136:139], v[190:193], v[34:37]
	v_mfma_f32_16x16x32_bf16 v[26:29], v[144:147], v[190:193], v[26:29]
	v_mfma_f32_16x16x32_bf16 v[18:21], v[136:139], v[198:201], v[18:21]
	v_mfma_f32_16x16x32_bf16 v[10:13], v[144:147], v[198:201], v[10:13]
	s_barrier
	s_add_i32 s4, s5, s3
	s_add_i32 m0, s4, 0xffffff80
	s_nop 0
	global_load_lds_dwordx4 v[244:245], off offset:128
	s_add_i32 m0, s4, 0x1f80
	s_nop 0
	global_load_lds_dwordx4 v[246:247], off offset:128
	s_waitcnt vmcnt(6)
	s_barrier
	v_mfma_f32_16x16x32_bf16 v[54:57], v[202:205], v[148:151], v[54:57]
	v_mfma_f32_16x16x32_bf16 v[50:53], v[210:213], v[148:151], v[50:53]
	v_mfma_f32_16x16x32_bf16 v[38:41], v[202:205], v[178:181], v[38:41]
	v_mfma_f32_16x16x32_bf16 v[30:33], v[210:213], v[178:181], v[30:33]
	v_mfma_f32_16x16x32_bf16 v[22:25], v[202:205], v[186:189], v[22:25]
	v_mfma_f32_16x16x32_bf16 v[14:17], v[210:213], v[186:189], v[14:17]
	v_mfma_f32_16x16x32_bf16 v[6:9], v[202:205], v[194:197], v[6:9]
	v_mfma_f32_16x16x32_bf16 v[2:5], v[210:213], v[194:197], v[2:5]
	v_mfma_f32_16x16x32_bf16 v[54:57], v[206:209], v[152:155], v[54:57]
	v_mfma_f32_16x16x32_bf16 v[50:53], v[214:217], v[152:155], v[50:53]
	v_mfma_f32_16x16x32_bf16 v[38:41], v[206:209], v[182:185], v[38:41]
	v_mfma_f32_16x16x32_bf16 v[30:33], v[214:217], v[182:185], v[30:33]
	v_mfma_f32_16x16x32_bf16 v[22:25], v[206:209], v[190:193], v[22:25]
	v_mfma_f32_16x16x32_bf16 v[14:17], v[214:217], v[190:193], v[14:17]
	v_mfma_f32_16x16x32_bf16 v[6:9], v[206:209], v[198:201], v[6:9]
	v_mfma_f32_16x16x32_bf16 v[2:5], v[214:217], v[198:201], v[2:5]
	s_add_u32 s6, s6, 0x100
	s_addc_u32 s7, s7, 0
	v_lshl_add_u64 v[130:131], v[130:131], 0, s[86:87]
	s_cmp_ge_u32 s42, s13
	s_mov_b32 s4, s42
	s_barrier
	s_cbranch_scc0 .LBB0_649
	s_lshl_b32 s6, s23, 8
	v_lshl_or_b32 v178, s22, 8, v238
	v_add_u32_e32 v130, s6, v1
	v_ashrrev_i32_e32 v179, 31, v178
	v_lshlrev_b64 v[186:187], 1, v[178:179]
	v_ashrrev_i32_e32 v131, 31, v130
	v_lshl_add_u64 v[190:191], s[18:19], 0, v[186:187]
	v_lshlrev_b64 v[188:189], 11, v[130:131]
	v_lshl_add_u64 v[132:133], v[190:191], 0, v[188:189]
	global_load_dwordx4 v[192:195], v[132:133], off
	global_load_dwordx4 v[154:157], v[132:133], off offset:256
	v_or_b32_e32 v132, 16, v130
	v_ashrrev_i32_e32 v133, 31, v132
	v_lshlrev_b64 v[184:185], 11, v[132:133]
	v_lshl_add_u64 v[132:133], v[190:191], 0, v[184:185]
	global_load_dwordx4 v[150:153], v[132:133], off
	global_load_dwordx4 v[146:149], v[132:133], off offset:256
	v_or_b32_e32 v132, 32, v130
	v_ashrrev_i32_e32 v133, 31, v132
	v_lshlrev_b64 v[182:183], 11, v[132:133]
	v_or_b32_e32 v130, 48, v130
	v_lshl_add_u64 v[132:133], v[190:191], 0, v[182:183]
	v_ashrrev_i32_e32 v131, 31, v130
	global_load_dwordx4 v[142:145], v[132:133], off
	global_load_dwordx4 v[138:141], v[132:133], off offset:256
	v_lshlrev_b64 v[180:181], 11, v[130:131]
	v_lshl_add_u64 v[130:131], v[190:191], 0, v[180:181]
	global_load_dwordx4 v[134:137], v[130:131], off
	s_nop 0
	global_load_dwordx4 v[130:133], v[130:131], off offset:256
	v_mov_b32_e32 v169, v168
	s_mov_b64 s[4:5], 0x40000
	v_cmp_lt_i32_e32 vcc, v227, v222
	s_waitcnt vmcnt(7)
	v_lshlrev_b32_e32 v196, 16, v192
	v_and_b32_e32 v197, 0xffff0000, v192
	v_lshlrev_b32_e32 v192, 16, v193
	v_and_b32_e32 v193, 0xffff0000, v193
	v_lshlrev_b32_e32 v198, 16, v194
	v_and_b32_e32 v199, 0xffff0000, v194
	v_lshlrev_b32_e32 v194, 16, v195
	v_and_b32_e32 v195, 0xffff0000, v195
	v_pk_fma_f32 v[128:129], v[168:169], v[128:129], v[192:193]
	v_pk_fma_f32 v[126:127], v[170:171], v[126:127], v[196:197]
	v_pk_fma_f32 v[192:193], v[168:169], v[124:125], v[194:195]
	v_pk_fma_f32 v[124:125], v[170:171], v[122:123], v[198:199]
	v_mul_f32_e32 v122, v127, v127
	v_mul_f32_e32 v123, v129, v129
	v_fmac_f32_e32 v122, v126, v126
	v_fmac_f32_e32 v123, v128, v128
	v_add_f32_e32 v122, v122, v123
	v_mul_f32_e32 v123, v125, v125
	v_mul_f32_e32 v194, v193, v193
	v_fmac_f32_e32 v123, v124, v124
	v_fmac_f32_e32 v194, v192, v192
	v_add_f32_e32 v123, v123, v194
	v_add_f32_e32 v194, v122, v123
	v_cvt_pk_bf16_f32 v122, v126, v127
	v_cvt_pk_bf16_f32 v123, v128, v129
	s_waitcnt vmcnt(6)
	v_lshlrev_b32_e32 v126, 16, v154
	v_and_b32_e32 v127, 0xffff0000, v154
	v_lshlrev_b32_e32 v128, 16, v155
	v_and_b32_e32 v129, 0xffff0000, v155
	v_lshlrev_b32_e32 v154, 16, v156
	v_and_b32_e32 v155, 0xffff0000, v156
	v_lshlrev_b32_e32 v156, 16, v157
	v_and_b32_e32 v157, 0xffff0000, v157
	v_pk_fma_f32 v[120:121], v[168:169], v[120:121], v[128:129]
	v_pk_fma_f32 v[118:119], v[170:171], v[118:119], v[126:127]
	v_pk_fma_f32 v[126:127], v[168:169], v[116:117], v[156:157]
	v_pk_fma_f32 v[116:117], v[170:171], v[114:115], v[154:155]
	v_mul_f32_e32 v114, v119, v119
	v_mul_f32_e32 v115, v121, v121
	v_fmac_f32_e32 v114, v118, v118
	v_fmac_f32_e32 v115, v120, v120
	v_add_f32_e32 v114, v114, v115
	v_mul_f32_e32 v115, v117, v117
	v_mul_f32_e32 v128, v127, v127
	v_fmac_f32_e32 v115, v116, v116
	v_fmac_f32_e32 v128, v126, v126
	v_add_f32_e32 v115, v115, v128
	v_add_f32_e32 v114, v114, v115
	v_cvt_pk_bf16_f32 v124, v124, v125
	v_cvt_pk_bf16_f32 v125, v192, v193
	v_add_f32_e32 v244, v194, v114
	v_cvt_pk_bf16_f32 v114, v118, v119
	v_cvt_pk_bf16_f32 v115, v120, v121
	s_waitcnt vmcnt(5)
	v_lshlrev_b32_e32 v118, 16, v150
	v_and_b32_e32 v119, 0xffff0000, v150
	v_lshlrev_b32_e32 v120, 16, v151
	v_and_b32_e32 v121, 0xffff0000, v151
	v_pk_fma_f32 v[154:155], v[168:169], v[112:113], v[120:121]
	v_pk_fma_f32 v[156:157], v[170:171], v[110:111], v[118:119]
	s_waitcnt vmcnt(4)
	v_lshlrev_b32_e32 v110, 16, v146
	v_and_b32_e32 v111, 0xffff0000, v146
	v_lshlrev_b32_e32 v112, 16, v147
	v_and_b32_e32 v113, 0xffff0000, v147
	v_lshlrev_b32_e32 v118, 16, v148
	v_and_b32_e32 v119, 0xffff0000, v148
	v_lshlrev_b32_e32 v120, 16, v149
	v_and_b32_e32 v121, 0xffff0000, v149
	v_pk_fma_f32 v[146:147], v[168:169], v[104:105], v[112:113]
	v_pk_fma_f32 v[192:193], v[170:171], v[102:103], v[110:111]
	v_pk_fma_f32 v[148:149], v[168:169], v[96:97], v[120:121]
	v_pk_fma_f32 v[198:199], v[170:171], v[94:95], v[118:119]
	s_waitcnt vmcnt(3)
	v_lshlrev_b32_e32 v94, 16, v142
	v_and_b32_e32 v95, 0xffff0000, v142
	v_lshlrev_b32_e32 v96, 16, v143
	v_and_b32_e32 v97, 0xffff0000, v143
	v_lshlrev_b32_e32 v110, 16, v144
	v_and_b32_e32 v111, 0xffff0000, v144
	v_lshlrev_b32_e32 v112, 16, v145
	v_and_b32_e32 v113, 0xffff0000, v145
	v_pk_fma_f32 v[142:143], v[168:169], v[100:101], v[96:97]
	v_pk_fma_f32 v[194:195], v[170:171], v[98:99], v[94:95]
	v_pk_fma_f32 v[144:145], v[168:169], v[92:93], v[112:113]
	v_pk_fma_f32 v[196:197], v[170:171], v[90:91], v[110:111]
	s_waitcnt vmcnt(2)
	v_lshlrev_b32_e32 v90, 16, v138
	v_and_b32_e32 v91, 0xffff0000, v138
	v_lshlrev_b32_e32 v92, 16, v139
	v_and_b32_e32 v93, 0xffff0000, v139
	v_lshlrev_b32_e32 v98, 16, v140
	v_and_b32_e32 v99, 0xffff0000, v140
	v_lshlrev_b32_e32 v100, 16, v141
	v_and_b32_e32 v101, 0xffff0000, v141
	v_pk_fma_f32 v[200:201], v[168:169], v[88:89], v[92:93]
	v_pk_fma_f32 v[208:209], v[170:171], v[86:87], v[90:91]
	v_pk_fma_f32 v[204:205], v[168:169], v[80:81], v[100:101]
	v_pk_fma_f32 v[210:211], v[170:171], v[78:79], v[98:99]
	s_waitcnt vmcnt(1)
	v_lshlrev_b32_e32 v78, 16, v134
	v_and_b32_e32 v79, 0xffff0000, v134
	v_lshlrev_b32_e32 v80, 16, v135
	v_and_b32_e32 v81, 0xffff0000, v135
	v_lshlrev_b32_e32 v86, 16, v136
	v_and_b32_e32 v87, 0xffff0000, v136
	v_lshlrev_b32_e32 v88, 16, v137
	v_and_b32_e32 v89, 0xffff0000, v137
	v_cvt_pk_bf16_f32 v116, v116, v117
	v_cvt_pk_bf16_f32 v117, v126, v127
	v_lshlrev_b32_e32 v126, 16, v152
	v_and_b32_e32 v127, 0xffff0000, v152
	v_lshlrev_b32_e32 v128, 16, v153
	v_and_b32_e32 v129, 0xffff0000, v153
	v_pk_fma_f32 v[138:139], v[168:169], v[84:85], v[80:81]
	v_pk_fma_f32 v[202:203], v[170:171], v[82:83], v[78:79]
	v_pk_fma_f32 v[140:141], v[168:169], v[76:77], v[88:89]
	v_pk_fma_f32 v[206:207], v[170:171], v[74:75], v[86:87]
	s_waitcnt vmcnt(0)
	v_lshlrev_b32_e32 v74, 16, v130
	v_and_b32_e32 v75, 0xffff0000, v130
	v_lshlrev_b32_e32 v76, 16, v131
	v_and_b32_e32 v77, 0xffff0000, v131
	v_lshlrev_b32_e32 v78, 16, v132
	v_and_b32_e32 v79, 0xffff0000, v132
	v_lshlrev_b32_e32 v80, 16, v133
	v_and_b32_e32 v81, 0xffff0000, v133
	v_lshl_add_u64 v[136:137], v[188:189], 0, s[4:5]
	s_mov_b64 s[4:5], 0x48000
	v_pk_fma_f32 v[150:151], v[168:169], v[108:109], v[128:129]
	v_pk_fma_f32 v[152:153], v[170:171], v[106:107], v[126:127]
	v_cvt_pk_bf16_f32 v106, v156, v157
	v_cvt_pk_bf16_f32 v107, v154, v155
	v_pk_fma_f32 v[212:213], v[168:169], v[72:73], v[76:77]
	v_cvt_pk_bf16_f32 v108, v152, v153
	v_cvt_pk_bf16_f32 v109, v150, v151
	v_cvt_pk_bf16_f32 v102, v192, v193
	v_cvt_pk_bf16_f32 v103, v146, v147
	v_cvt_pk_bf16_f32 v104, v198, v199
	v_cvt_pk_bf16_f32 v105, v148, v149
	v_cvt_pk_bf16_f32 v94, v194, v195
	v_cvt_pk_bf16_f32 v95, v142, v143
	v_cvt_pk_bf16_f32 v96, v196, v197
	v_cvt_pk_bf16_f32 v97, v144, v145
	v_cvt_pk_bf16_f32 v118, v208, v209
	v_cvt_pk_bf16_f32 v119, v200, v201
	v_cvt_pk_bf16_f32 v120, v210, v211
	v_cvt_pk_bf16_f32 v121, v204, v205
	v_cvt_pk_bf16_f32 v98, v202, v203
	v_cvt_pk_bf16_f32 v99, v138, v139
	v_cvt_pk_bf16_f32 v100, v206, v207
	v_cvt_pk_bf16_f32 v101, v140, v141
	v_pk_fma_f32 v[216:217], v[170:171], v[70:71], v[74:75]
	v_pk_fma_f32 v[214:215], v[168:169], v[68:69], v[80:81]
	v_pk_fma_f32 v[218:219], v[170:171], v[66:67], v[78:79]
	v_cvt_pk_bf16_f32 v126, v216, v217
	v_cvt_pk_bf16_f32 v127, v212, v213
	v_lshl_add_u64 v[66:67], v[190:191], 0, v[136:137]
	v_cvt_pk_bf16_f32 v128, v218, v219
	v_cvt_pk_bf16_f32 v129, v214, v215
	v_lshl_add_u64 v[134:135], v[188:189], 0, s[4:5]
	s_mov_b64 s[4:5], 0x50000
	global_load_dwordx4 v[110:113], v[66:67], off
	global_load_dwordx4 v[90:93], v[66:67], off offset:256
	v_lshl_add_u64 v[66:67], v[190:191], 0, v[134:135]
	v_lshl_add_u64 v[132:133], v[188:189], 0, s[4:5]
	s_mov_b64 s[4:5], 0x58000
	global_load_dwordx4 v[86:89], v[66:67], off
	global_load_dwordx4 v[82:85], v[66:67], off offset:256
	v_lshl_add_u64 v[66:67], v[190:191], 0, v[132:133]
	v_lshl_add_u64 v[130:131], v[188:189], 0, s[4:5]
	global_load_dwordx4 v[78:81], v[66:67], off
	global_load_dwordx4 v[74:77], v[66:67], off offset:256
	v_lshl_add_u64 v[66:67], v[190:191], 0, v[130:131]
	global_load_dwordx4 v[70:73], v[66:67], off
	s_nop 0
	global_load_dwordx4 v[66:69], v[66:67], off offset:256
	v_cndmask_b32_e32 v169, v221, v227, vcc
	v_lshl_add_u64 v[188:189], s[18:19], 0, v[188:189]
	v_lshlrev_b32_e32 v190, 2, v169
	v_lshl_add_u64 v[186:187], v[188:189], 0, v[186:187]
	global_store_dwordx4 v[186:187], v[122:125], off
	global_store_dwordx4 v[186:187], v[114:117], off offset:256
	s_nop 1
	v_mov_b32_e32 v114, v244
	s_nop 1
	v_permlane16_swap_b32_e32 v114, v244
	v_cmp_lt_i32_e32 vcc, v228, v222
	s_waitcnt lgkmcnt(0)
	v_add_f32_e32 v114, v244, v114
	v_cndmask_b32_e32 v169, v221, v228, vcc
	v_lshlrev_b32_e32 v191, 2, v169
	v_mov_b32_e32 v115, v114
	s_nop 1
	v_permlane32_swap_b32_e32 v115, v114
	s_and_saveexec_b64 s[4:5], s[38:39]
	s_cbranch_execz .LBB0_652
	s_waitcnt lgkmcnt(0)
	v_add_f32_e32 v114, v114, v115
	v_add_u32_e32 v115, s90, v239
	ds_write_b32 v115, v114
